# prep_row: row-invariant weight loads hoisted + next-row prefetch; P5 epilogue priority split
# speedup vs baseline: 1.0011x; 1.0011x over previous
.LBB0_989:
	s_lshl_b32 s3, s3, 3
	s_add_i32 s12, s16, s3
	s_cmpk_gt_i32 s12, 0x1fff
	s_cbranch_scc1 .LBB0_998
	v_and_b32_e32 v2, 64, v233
	v_add_u32_e32 v2, 64, v2
	v_xor_b32_e32 v3, 1, v233
	v_cmp_lt_i32_e32 vcc, v3, v2
	v_readlane_b32 s4, v255, 51
	v_lshlrev_b32_e32 v18, 4, v54
	v_cndmask_b32_e32 v3, v233, v3, vcc
	v_lshlrev_b32_e32 v48, 2, v3
	v_xor_b32_e32 v3, 2, v233
	v_cmp_lt_i32_e32 vcc, v3, v2
	v_readlane_b32 s5, v255, 52
	s_lshl_b32 s18, s4, 9
	v_cndmask_b32_e32 v3, v233, v3, vcc
	v_lshlrev_b32_e32 v49, 2, v3
	v_xor_b32_e32 v3, 4, v233
	v_cmp_lt_i32_e32 vcc, v3, v2
	s_mul_i32 s3, s4, 0xc0
	s_lshl_b32 s4, s4, 7
	v_cndmask_b32_e32 v3, v233, v3, vcc
	v_lshlrev_b32_e32 v50, 2, v3
	v_xor_b32_e32 v3, 8, v233
	v_cmp_lt_i32_e32 vcc, v3, v2
	s_ashr_i32 s13, s12, 31
	s_lshl_b32 s14, s0, 3
	v_cndmask_b32_e32 v3, v233, v3, vcc
	v_lshlrev_b32_e32 v51, 2, v3
	v_xor_b32_e32 v3, 16, v233
	v_cmp_lt_i32_e32 vcc, v3, v2
	v_ashrrev_i32_e32 v19, 31, v18
	s_ashr_i32 s19, s18, 31
	v_cndmask_b32_e32 v3, v233, v3, vcc
	v_lshlrev_b32_e32 v52, 2, v3
	v_xor_b32_e32 v3, 32, v233
	v_cmp_lt_i32_e32 vcc, v3, v2
	s_addk_i32 s3, 0x80
	s_ashr_i32 s5, s4, 31
	v_cndmask_b32_e32 v2, v233, v3, vcc
	v_lshlrev_b32_e32 v53, 2, v2
	v_lshlrev_b32_e32 v2, 1, v54
	s_lshl_b64 s[6:7], s[12:13], 2
	v_add_u32_e32 v20, s3, v54
	v_and_b32_e32 v8, 56, v2
	v_ashrrev_i32_e32 v2, 3, v54
	s_add_u32 s3, s6, 0x48700000
	v_lshlrev_b64 v[6:7], 1, v[18:19]
	v_mov_b32_e32 v10, 0x6a00
	v_ashrrev_i32_e32 v3, 31, v2
	s_addc_u32 s9, s7, 0
	s_ashr_i32 s15, s14, 31
	v_mad_i64_i32 v[22:23], s[6:7], s12, v10, v[6:7]
	v_and_b32_e32 v9, -4, v2
	v_lshlrev_b64 v[2:3], 21, v[2:3]
	s_lshl_b64 s[20:21], s[14:15], 2
	s_lshl_b64 s[6:7], s[12:13], 8
	s_lshl_b64 s[26:27], s[14:15], 8
	s_lshl_b64 s[24:25], s[12:13], 11
	s_lshl_b64 s[44:45], s[14:15], 11
	v_lshl_add_u64 v[24:25], v[2:3], 0, s[6:7]
	v_and_b32_e32 v2, 7, v54
	v_lshl_add_u64 v[26:27], s[24:25], 0, v[6:7]
	s_add_u32 s24, s6, 0x48500000
	v_and_b32_e32 v5, 31, v54
	s_mul_i32 s31, s12, 0x6a00
	v_lshl_or_b32 v24, v2, 5, v24
	s_addc_u32 s25, s7, 0
	v_add_u32_e32 v2, v8, v9
	s_load_dwordx2 s[16:17], s[10:11], 0xb0
	s_mul_hi_i32 s30, s12, 0x6a00
	v_and_or_b32 v2, v54, 3, v2
	v_lshl_or_b32 v30, v5, 2, s6
	s_add_u32 s6, s31, 0x23d06800
	v_ashrrev_i32_e32 v3, 31, v2
	v_mov_b32_e32 v31, s7
	s_addc_u32 s7, s30, 0
	v_lshl_add_u64 v[28:29], v[2:3], 2, s[24:25]
	v_lshl_add_u64 v[2:3], s[6:7], 0, v[6:7]
	v_mad_i64_i32 v[6:7], s[6:7], v54, 30, 0
	s_waitcnt lgkmcnt(0)
	v_and_b32_e32 v4, 0x70, v18
	v_sub_co_u32_e32 v32, vcc, v2, v6
	v_cmp_gt_i32_e64 s[38:39], 32, v54
	v_cmp_lt_i32_e64 s[40:41], 31, v54
	v_mov_b32_e32 v98, v18
	v_ashrrev_i32_e32 v21, 31, v20
	v_cmp_eq_u32_e64 s[42:43], 0, v54
	s_mul_i32 s22, s0, 0x35000
	s_mul_hi_i32 s23, s14, 0x6a00
	v_subb_co_u32_e32 v33, vcc, v3, v7, vcc
	s_lshl_b64 s[46:47], s[4:5], 2
	v_lshlrev_b32_e32 v54, 2, v4
	s_and_saveexec_b64 s[4:5], s[40:41]
	s_xor_b64 s[4:5], exec, s[4:5]
	s_cbranch_execz .Lpr_h1
	s_load_dwordx2 s[6:7], s[10:11], 0x30
	s_lshl_b64 s[24:25], s[18:19], 2
	s_waitcnt lgkmcnt(0)
	s_add_u32 s6, s6, s24
	s_addc_u32 s7, s7, s25
	v_lshl_add_u64 v[198:199], v[98:99], 2, s[6:7]
	s_movk_i32 s6, 0xf800
	s_mov_b32 s7, -1
	v_lshl_add_u64 v[198:199], v[198:199], 0, s[6:7]
.Lpr_h1:
	s_andn2_saveexec_b64 s[4:5], s[4:5]
	s_cbranch_execz .Lpr_h2
	s_load_dwordx2 s[6:7], s[10:11], 0x20
	s_lshl_b64 s[24:25], s[18:19], 2
	s_waitcnt lgkmcnt(0)
	s_add_u32 s6, s6, s24
	s_addc_u32 s7, s7, s25
	v_lshl_add_u64 v[198:199], v[18:19], 2, s[6:7]
.Lpr_h2:
	s_or_b64 exec, exec, s[4:5]
	global_load_dwordx4 v[100:103], v[198:199], off offset:48
	global_load_dwordx4 v[104:107], v[198:199], off offset:16
	global_load_dwordx4 v[108:111], v[198:199], off offset:32
	global_load_dwordx4 v[112:115], v[198:199], off
	s_load_dwordx4 s[4:7], s[10:11], 0x68
	s_waitcnt lgkmcnt(0)
	s_add_u32 s4, s4, s46
	s_addc_u32 s5, s5, s47
	s_nop 1
	global_load_dwordx4 v[116:119], v54, s[4:5] offset:48
	global_load_dwordx4 v[120:123], v54, s[4:5] offset:16
	global_load_dwordx4 v[124:127], v54, s[4:5] offset:32
	global_load_dwordx4 v[128:131], v54, s[4:5]
	s_add_u32 s4, s6, s46
	s_addc_u32 s5, s7, s47
	s_nop 1
	global_load_dwordx4 v[152:155], v54, s[4:5] offset:48
	global_load_dwordx4 v[156:159], v54, s[4:5] offset:16
	global_load_dwordx4 v[160:163], v54, s[4:5] offset:32
	global_load_dwordx4 v[164:167], v54, s[4:5]
	s_load_dwordx2 s[4:5], s[10:11], 0x48
	s_waitcnt lgkmcnt(0)
	v_lshl_add_u64 v[198:199], v[20:21], 2, s[4:5]
	global_load_dword v151, v[198:199], off
	v_lshl_add_u64 v[196:197], s[16:17], 0, v[22:23]
	s_mov_b64 s[4:5], 0x23d00000
	v_lshl_add_u64 v[198:199], v[196:197], 0, s[4:5]
	global_load_dwordx4 v[168:171], v[198:199], off
	global_load_dwordx4 v[172:175], v[198:199], off offset:16
	s_mov_b64 s[4:5], 0x23d02000
	v_lshl_add_u64 v[198:199], v[196:197], 0, s[4:5]
	global_load_dwordx4 v[176:179], v[198:199], off
	global_load_dwordx4 v[180:183], v[198:199], off offset:16
	global_load_dwordx4 v[184:187], v[198:199], off offset:2048
	s_mov_b64 s[4:5], 0x23d02800
	v_lshl_add_u64 v[198:199], v[196:197], 0, s[4:5]
	global_load_dwordx4 v[188:191], v[198:199], off offset:16
	v_lshl_add_u64 v[198:199], s[16:17], 0, v[32:33]
	global_load_ushort v192, v[198:199], off
	v_lshl_add_u64 v[198:199], s[16:17], 0, v[30:31]
	s_mov_b64 s[4:5], 0x48300000
	v_lshl_add_u64 v[198:199], v[198:199], 0, s[4:5]
	global_load_dword v193, v[198:199], off
	global_load_dword v194, v[198:199], off offset:128
	s_waitcnt vmcnt(0)
	s_branch .Lpr_go
.LBB0_991:
	s_or_b64 exec, exec, s[4:5]
	v_lshlrev_b32_e32 v42, 16, v10
	v_and_b32_e32 v43, 0xffff0000, v10
	v_lshlrev_b32_e32 v44, 16, v14
	v_and_b32_e32 v45, 0xffff0000, v14
	v_pk_mul_f32 v[34:35], v[42:43], v[42:43]
	v_and_b32_e32 v38, 0xffff0000, v11
	v_lshlrev_b32_e32 v39, 16, v11
	v_pk_fma_f32 v[46:47], v[44:45], v[44:45], v[34:35]
	v_and_b32_e32 v40, 0xffff0000, v15
	v_lshlrev_b32_e32 v41, 16, v15
	v_pk_mul_f32 v[10:11], v[38:39], v[38:39]
	v_and_b32_e32 v36, 0xffff0000, v16
	v_pk_fma_f32 v[56:57], v[40:41], v[40:41], v[10:11]
	v_lshlrev_b32_e32 v37, 16, v16
	v_and_b32_e32 v34, 0xffff0000, v12
	v_lshlrev_b32_e32 v35, 16, v12
	v_add_f32_e32 v16, v46, v47
	v_pk_mul_f32 v[10:11], v[34:35], v[34:35]
	v_add_f32_e32 v16, v57, v16
	v_pk_fma_f32 v[58:59], v[36:37], v[36:37], v[10:11]
	v_add_f32_e32 v16, v56, v16
	s_waitcnt lgkmcnt(0)
	v_add_f32_e32 v16, v59, v16
	v_add_f32_e32 v16, v58, v16
	v_mov_b32_e32 v56, v116
	v_mov_b32_e32 v57, v117
	v_mov_b32_e32 v58, v118
	v_mov_b32_e32 v59, v119
	v_mov_b32_e32 v60, v120
	v_mov_b32_e32 v61, v121
	v_mov_b32_e32 v62, v122
	v_mov_b32_e32 v63, v123
	v_mov_b32_e32 v64, v124
	v_mov_b32_e32 v65, v125
	v_mov_b32_e32 v66, v126
	v_mov_b32_e32 v67, v127
	v_mov_b32_e32 v68, v128
	v_mov_b32_e32 v69, v129
	v_mov_b32_e32 v70, v130
	v_mov_b32_e32 v71, v131
	v_and_b32_e32 v10, 0xffff0000, v13
	v_lshlrev_b32_e32 v11, 16, v13
	v_and_b32_e32 v14, 0xffff0000, v17
	v_lshlrev_b32_e32 v15, 16, v17
	v_pk_mul_f32 v[12:13], v[10:11], v[10:11]
	s_mov_b32 s0, 0x3f100000
	v_pk_fma_f32 v[12:13], v[14:15], v[14:15], v[12:13]
	v_add_f32_e32 v13, v13, v16
	v_add_f32_e32 v12, v12, v13
	ds_bpermute_b32 v13, v48, v12
	s_add_i32 s12, s12, s14
	s_add_u32 s3, s3, s20
	s_addc_u32 s9, s9, s21
	s_waitcnt lgkmcnt(0)
	v_add_f32_e32 v12, v12, v13
	ds_bpermute_b32 v13, v49, v12
	v_lshl_add_u64 v[22:23], v[22:23], 0, s[22:23]
	v_lshl_add_u64 v[26:27], v[26:27], 0, s[44:45]
	v_lshl_add_u64 v[28:29], v[28:29], 0, s[26:27]
	v_lshl_add_u64 v[30:31], v[30:31], 0, s[26:27]
	s_waitcnt lgkmcnt(0)
	v_add_f32_e32 v12, v12, v13
	ds_bpermute_b32 v13, v50, v12
	v_lshl_add_u64 v[32:33], v[32:33], 0, s[22:23]
	s_cmpk_lt_i32 s12, 0x2000
	s_waitcnt lgkmcnt(0)
	v_add_f32_e32 v12, v12, v13
	v_fmamk_f32 v12, v12, 0x3c000000, v1
	v_cmp_gt_f32_e32 vcc, s37, v12
	v_mul_f32_e32 v13, 0x4b800000, v12
	s_nop 0
	v_cndmask_b32_e32 v12, v12, v13, vcc
	v_rsq_f32_e32 v12, v12
	s_nop 0
	v_mul_f32_e32 v13, 0x45800000, v12
	v_cndmask_b32_e32 v12, v12, v13, vcc
	v_mul_f32_e32 v17, v65, v12
	v_mul_f32_e32 v43, v17, v43
	v_mul_f32_e32 v17, v70, v12
	v_mul_f32_e32 v17, v17, v41
	v_mul_f32_e32 v41, v66, v12
	v_mul_f32_e32 v39, v41, v39
	v_mul_f32_e32 v41, v71, v12
	v_mul_f32_e32 v40, v41, v40
	v_mul_f32_e32 v41, v12, v67
	v_mul_f32_e32 v38, v41, v38
	v_mul_f32_e32 v41, v12, v60
	v_mul_f32_e32 v37, v41, v37
	v_mul_f32_e32 v41, v12, v56
	v_mul_f32_e32 v35, v41, v35
	v_mul_f32_e32 v41, v12, v61
	v_mul_f32_e32 v36, v41, v36
	v_mul_f32_e32 v41, v12, v57
	v_mul_f32_e32 v34, v41, v34
	v_mul_f32_e32 v41, v12, v62
	v_mul_f32_e32 v15, v41, v15
	v_mul_f32_e32 v41, v12, v58
	v_mul_f32_e32 v13, v68, v12
	v_mul_f32_e32 v16, v64, v12
	v_mul_f32_e32 v41, v41, v11
	v_mul_f32_e32 v11, v12, v63
	v_mul_f32_e32 v13, v13, v44
	v_mul_f32_e32 v42, v16, v42
	v_mul_f32_e32 v16, v69, v12
	v_mul_f32_e32 v44, v11, v14
	v_mul_f32_e32 v11, v12, v59
	v_mul_f32_e32 v16, v16, v45
	v_mul_f32_e32 v45, v11, v10
	v_lshl_add_u64 v[10:11], s[16:17], 0, v[24:25]
	v_cvt_pk_bf16_f32 v12, v13, v16
	v_add_co_u32_e32 v16, vcc, s0, v10
	v_cvt_pk_bf16_f32 v13, v17, v40
	v_cvt_pk_bf16_f32 v14, v37, v36
	v_cvt_pk_bf16_f32 v15, v15, v44
	v_lshlrev_b32_e32 v40, 16, v2
	s_nop 0
	v_addc_co_u32_e32 v17, vcc, 0, v11, vcc
	global_store_dwordx4 v[16:17], v[12:15], off
	v_and_b32_e32 v36, 0xffff0000, v3
	v_lshlrev_b32_e32 v37, 16, v3
	v_cvt_pk_bf16_f32 v12, v42, v43
	v_cvt_pk_bf16_f32 v13, v39, v38
	v_cvt_pk_bf16_f32 v14, v35, v34
	v_cvt_pk_bf16_f32 v15, v41, v45
	v_and_b32_e32 v41, 0xffff0000, v2
	global_store_dwordx4 v[16:17], v[12:15], off offset:16
	v_lshlrev_b32_e32 v42, 16, v6
	v_and_b32_e32 v43, 0xffff0000, v6
	v_pk_mul_f32 v[12:13], v[40:41], v[40:41]
	v_and_b32_e32 v38, 0xffff0000, v7
	v_pk_fma_f32 v[44:45], v[42:43], v[42:43], v[12:13]
	v_lshlrev_b32_e32 v39, 16, v7
	v_pk_mul_f32 v[2:3], v[36:37], v[36:37]
	v_and_b32_e32 v34, 0xffff0000, v8
	v_pk_fma_f32 v[2:3], v[38:39], v[38:39], v[2:3]
	v_lshlrev_b32_e32 v35, 16, v8
	v_and_b32_e32 v16, 0xffff0000, v4
	v_lshlrev_b32_e32 v17, 16, v4
	v_add_f32_e32 v8, v44, v45
	v_pk_mul_f32 v[6:7], v[16:17], v[16:17]
	v_add_f32_e32 v3, v3, v8
	v_pk_fma_f32 v[6:7], v[34:35], v[34:35], v[6:7]
	v_and_b32_e32 v12, 0xffff0000, v5
	v_lshlrev_b32_e32 v13, 16, v5
	v_add_f32_e32 v2, v2, v3
	v_and_b32_e32 v14, 0xffff0000, v9
	v_lshlrev_b32_e32 v15, 16, v9
	v_pk_mul_f32 v[4:5], v[12:13], v[12:13]
	v_add_f32_e32 v2, v7, v2
	v_pk_fma_f32 v[4:5], v[14:15], v[14:15], v[4:5]
	v_add_f32_e32 v2, v6, v2
	v_add_f32_e32 v2, v5, v2
	v_add_f32_e32 v2, v4, v2
	ds_bpermute_b32 v3, v48, v2
	s_mov_b32 s0, 0x40100000
	v_lshl_add_u64 v[24:25], v[24:25], 0, s[26:27]
	s_waitcnt lgkmcnt(0)
	v_add_f32_e32 v2, v2, v3
	ds_bpermute_b32 v3, v49, v2
	s_waitcnt lgkmcnt(0)
	v_add_f32_e32 v2, v2, v3
	ds_bpermute_b32 v3, v50, v2
	s_waitcnt lgkmcnt(0)
	v_add_f32_e32 v2, v2, v3
	v_fmamk_f32 v2, v2, 0x3c000000, v1
	v_cmp_gt_f32_e32 vcc, s37, v2
	v_mul_f32_e32 v3, 0x4b800000, v2
	s_nop 0
	v_cndmask_b32_e32 v2, v2, v3, vcc
	v_rsq_f32_e32 v2, v2
	s_nop 0
	v_mul_f32_e32 v3, 0x45800000, v2
	v_cndmask_b32_e32 v44, v2, v3, vcc
	v_mov_b32_e32 v2, v152
	v_mov_b32_e32 v3, v153
	v_mov_b32_e32 v4, v154
	v_mov_b32_e32 v5, v155
	v_mov_b32_e32 v6, v156
	v_mov_b32_e32 v7, v157
	v_mov_b32_e32 v8, v158
	v_mov_b32_e32 v9, v159
	v_mov_b32_e32 v56, v160
	v_mov_b32_e32 v57, v161
	v_mov_b32_e32 v58, v162
	v_mov_b32_e32 v59, v163
	v_mov_b32_e32 v60, v164
	v_mov_b32_e32 v61, v165
	v_mov_b32_e32 v62, v166
	v_mov_b32_e32 v63, v167
	v_mul_f32_e32 v2, v44, v2
	v_mul_f32_e32 v17, v2, v17
	v_mul_f32_e32 v2, v44, v7
	v_mul_f32_e32 v45, v60, v44
	v_mul_f32_e32 v42, v45, v42
	v_mul_f32_e32 v45, v56, v44
	v_mul_f32_e32 v40, v45, v40
	v_mul_f32_e32 v45, v61, v44
	v_mul_f32_e32 v7, v2, v34
	v_mul_f32_e32 v2, v44, v3
	v_mul_f32_e32 v43, v45, v43
	v_mul_f32_e32 v45, v57, v44
	v_mul_f32_e32 v16, v2, v16
	v_mul_f32_e32 v2, v44, v8
	v_mul_f32_e32 v41, v45, v41
	v_mul_f32_e32 v45, v62, v44
	v_mul_f32_e32 v8, v2, v15
	v_mul_f32_e32 v2, v44, v4
	v_mul_f32_e32 v39, v45, v39
	v_mul_f32_e32 v45, v58, v44
	v_mul_f32_e32 v6, v44, v6
	v_mul_f32_e32 v13, v2, v13
	v_mul_f32_e32 v2, v44, v9
	v_mul_f32_e32 v37, v45, v37
	v_mul_f32_e32 v45, v63, v44
	v_mul_f32_e32 v6, v6, v35
	v_mul_f32_e32 v9, v2, v14
	v_mul_f32_e32 v2, v44, v5
	v_mul_f32_e32 v38, v45, v38
	v_mul_f32_e32 v12, v2, v12
	v_cvt_pk_bf16_f32 v2, v42, v43
	v_cvt_pk_bf16_f32 v3, v39, v38
	v_cvt_pk_bf16_f32 v4, v6, v7
	v_add_co_u32_e32 v6, vcc, s0, v10
	v_mul_f32_e32 v45, v44, v59
	v_cvt_pk_bf16_f32 v5, v8, v9
	s_nop 0
	v_addc_co_u32_e32 v7, vcc, 0, v11, vcc
	v_mul_f32_e32 v36, v45, v36
	global_store_dwordx4 v[6:7], v[2:5], off
	s_nop 1
	v_cvt_pk_bf16_f32 v2, v40, v41
	v_cvt_pk_bf16_f32 v3, v37, v36
	v_cvt_pk_bf16_f32 v4, v17, v16
	v_cvt_pk_bf16_f32 v5, v13, v12
	global_store_dwordx4 v[6:7], v[2:5], off offset:16
	s_cbranch_scc0 .LBB0_998

.Lpr_go:
	s_nop 1
	v_mov_b32_e32 v2, v188
	v_mov_b32_e32 v3, v189
	v_mov_b32_e32 v4, v190
	v_mov_b32_e32 v5, v191
	v_mov_b32_e32 v6, v184
	v_mov_b32_e32 v7, v185
	v_mov_b32_e32 v8, v186
	v_mov_b32_e32 v9, v187
	v_mov_b32_e32 v10, v180
	v_mov_b32_e32 v11, v181
	v_mov_b32_e32 v12, v182
	v_mov_b32_e32 v13, v183
	v_mov_b32_e32 v14, v176
	v_mov_b32_e32 v15, v177
	v_mov_b32_e32 v16, v178
	v_mov_b32_e32 v17, v179
	v_mov_b32_e32 v40, v168
	v_mov_b32_e32 v41, v169
	v_mov_b32_e32 v42, v170
	v_mov_b32_e32 v43, v171
	v_mov_b32_e32 v44, v172
	v_mov_b32_e32 v45, v173
	v_mov_b32_e32 v46, v174
	v_mov_b32_e32 v47, v175
	v_mov_b32_e32 v57, v192
	v_mov_b32_e32 v55, v193
	v_mov_b32_e32 v56, v194
	s_add_i32 s98, s12, s14
	s_cmpk_lt_i32 s98, 0x2000
	s_cbranch_scc0 .Lpr_nopf
	v_lshl_add_u64 v[196:197], v[22:23], 0, s[22:23]
	v_lshl_add_u64 v[196:197], s[16:17], 0, v[196:197]
	s_mov_b64 s[4:5], 0x23d00000
	v_lshl_add_u64 v[198:199], v[196:197], 0, s[4:5]
	global_load_dwordx4 v[168:171], v[198:199], off
	global_load_dwordx4 v[172:175], v[198:199], off offset:16
	s_mov_b64 s[4:5], 0x23d02000
	v_lshl_add_u64 v[198:199], v[196:197], 0, s[4:5]
	global_load_dwordx4 v[176:179], v[198:199], off
	global_load_dwordx4 v[180:183], v[198:199], off offset:16
	global_load_dwordx4 v[184:187], v[198:199], off offset:2048
	s_mov_b64 s[4:5], 0x23d02800
	v_lshl_add_u64 v[198:199], v[196:197], 0, s[4:5]
	global_load_dwordx4 v[188:191], v[198:199], off offset:16
	v_lshl_add_u64 v[198:199], v[32:33], 0, s[22:23]
	v_lshl_add_u64 v[198:199], s[16:17], 0, v[198:199]
	global_load_ushort v192, v[198:199], off
	v_lshl_add_u64 v[198:199], v[30:31], 0, s[26:27]
	v_lshl_add_u64 v[198:199], s[16:17], 0, v[198:199]
	s_mov_b64 s[4:5], 0x48300000
	v_lshl_add_u64 v[198:199], v[198:199], 0, s[4:5]
	global_load_dword v193, v[198:199], off
	global_load_dword v194, v[198:199], off offset:128
.Lpr_nopf:
	v_lshlrev_b32_e32 v60, 16, v40
	v_lshlrev_b32_e32 v61, 16, v44
	v_and_b32_e32 v59, 0xffff0000, v44
	v_and_b32_e32 v58, 0xffff0000, v40
	v_mul_f32_e32 v34, v61, v61
	v_mul_f32_e32 v35, v59, v59
	v_fmac_f32_e32 v34, v60, v60
	v_fmac_f32_e32 v35, v58, v58
	v_and_b32_e32 v36, 0xffff0000, v45
	v_lshlrev_b32_e32 v37, 16, v45
	v_add_f32_e32 v40, v34, v35
	v_and_b32_e32 v34, 0xffff0000, v41
	v_lshlrev_b32_e32 v35, 16, v41
	v_pk_mul_f32 v[38:39], v[36:37], v[36:37]
	v_lshlrev_b32_e32 v41, 16, v46
	v_pk_fma_f32 v[38:39], v[34:35], v[34:35], v[38:39]
	s_nop 0
	v_add_f32_e32 v39, v39, v40
	v_and_b32_e32 v40, 0xffff0000, v46
	v_add_f32_e32 v62, v38, v39
	v_and_b32_e32 v38, 0xffff0000, v42
	v_lshlrev_b32_e32 v39, 16, v42
	v_pk_mul_f32 v[44:45], v[40:41], v[40:41]
	s_nop 0
	v_pk_fma_f32 v[44:45], v[38:39], v[38:39], v[44:45]
	s_nop 0
	v_add_f32_e32 v42, v45, v62
	v_add_f32_e32 v62, v44, v42
	v_and_b32_e32 v44, 0xffff0000, v47
	v_lshlrev_b32_e32 v45, 16, v47
	v_and_b32_e32 v42, 0xffff0000, v43
	v_lshlrev_b32_e32 v43, 16, v43
	v_pk_mul_f32 v[46:47], v[44:45], v[44:45]
	s_nop 0
	v_pk_fma_f32 v[46:47], v[42:43], v[42:43], v[46:47]
	s_nop 0
	v_add_f32_e32 v47, v47, v62
	v_add_f32_e32 v46, v46, v47
	ds_bpermute_b32 v47, v48, v46
	s_waitcnt lgkmcnt(0)
	v_add_f32_e32 v46, v46, v47
	ds_bpermute_b32 v47, v49, v46
	s_waitcnt lgkmcnt(0)
	v_add_f32_e32 v46, v46, v47
	ds_bpermute_b32 v47, v50, v46
	s_waitcnt lgkmcnt(0)
	v_add_f32_e32 v46, v46, v47
	ds_bpermute_b32 v47, v51, v46
	s_waitcnt lgkmcnt(0)
	v_add_f32_e32 v62, v46, v47
	ds_bpermute_b32 v63, v52, v62
	s_waitcnt lgkmcnt(0)
	v_add_f32_e32 v62, v62, v63
	v_fmamk_f32 v62, v62, 0x3b000000, v1
	v_cmp_gt_f32_e32 vcc, s37, v62
	v_mul_f32_e32 v63, 0x4b800000, v62
	s_mov_b32 s0, 0x3a100000
	v_cndmask_b32_e32 v62, v62, v63, vcc
	v_rsq_f32_e32 v62, v62
	v_lshlrev_b32_e32 v57, 16, v57
	v_mul_f32_e32 v63, 0x45800000, v62
	v_cndmask_b32_e32 v78, v62, v63, vcc
	v_mov_b32_e32 v62, v100
	v_mov_b32_e32 v63, v101
	v_mov_b32_e32 v64, v102
	v_mov_b32_e32 v65, v103
	v_mov_b32_e32 v66, v104
	v_mov_b32_e32 v67, v105
	v_mov_b32_e32 v68, v106
	v_mov_b32_e32 v69, v107
	v_mov_b32_e32 v70, v108
	v_mov_b32_e32 v71, v109
	v_mov_b32_e32 v72, v110
	v_mov_b32_e32 v73, v111
	v_mov_b32_e32 v74, v112
	v_mov_b32_e32 v75, v113
	v_mov_b32_e32 v76, v114
	v_mov_b32_e32 v77, v115
	v_mul_f32_e32 v47, v78, v70
	v_mul_f32_e32 v46, v78, v74
	v_mul_f32_e32 v46, v46, v60
	v_mul_f32_e32 v60, v78, v75
	v_mul_f32_e32 v58, v60, v58
	v_mul_f32_e32 v60, v78, v71
	v_mul_f32_e32 v59, v60, v59
	v_mul_f32_e32 v60, v78, v76
	v_mul_f32_e32 v35, v60, v35
	v_mul_f32_e32 v60, v78, v72
	v_mul_f32_e32 v60, v60, v37
	v_mul_f32_e32 v37, v78, v77
	v_mul_f32_e32 v37, v37, v34
	v_mul_f32_e32 v34, v78, v73
	v_mul_f32_e32 v47, v47, v61
	v_mul_f32_e32 v61, v34, v36
	v_mul_f32_e32 v34, v78, v66
	v_mul_f32_e32 v36, v34, v39
	v_mul_f32_e32 v34, v78, v62
	v_mul_f32_e32 v41, v34, v41
	v_mul_f32_e32 v34, v78, v67
	v_mul_f32_e32 v62, v34, v38
	v_mul_f32_e32 v34, v78, v63
	v_mul_f32_e32 v40, v34, v40
	v_mul_f32_e32 v34, v78, v68
	v_mul_f32_e32 v43, v34, v43
	v_mul_f32_e32 v34, v78, v64
	v_mul_f32_e32 v45, v34, v45
	v_mul_f32_e32 v34, v78, v69
	v_lshl_add_u64 v[38:39], s[16:17], 0, v[26:27]
	v_mul_f32_e32 v42, v34, v42
	v_mul_f32_e32 v34, v78, v65
	v_add_co_u32_e32 v38, vcc, s0, v38
	v_mul_f32_e32 v44, v34, v44
	v_cvt_pk_bf16_f32 v34, v46, v58
	v_cvt_pk_bf16_f32 v35, v35, v37
	v_cvt_pk_bf16_f32 v36, v36, v62
	v_cvt_pk_bf16_f32 v37, v43, v42
	s_nop 0
	v_addc_co_u32_e32 v39, vcc, 0, v39, vcc
	global_store_dwordx4 v[38:39], v[34:37], off
	s_nop 1
	v_cvt_pk_bf16_f32 v34, v47, v59
	v_cvt_pk_bf16_f32 v35, v60, v61
	v_cvt_pk_bf16_f32 v36, v41, v40
	v_cvt_pk_bf16_f32 v37, v45, v44
	global_store_dwordx4 v[38:39], v[34:37], off offset:16
	s_nop 0
	s_nop 0
	v_mul_f32_e32 v34, v57, v57
	ds_bpermute_b32 v34, v48, v34
	s_waitcnt lgkmcnt(0)
	v_mov_b32_e32 v36, v151
	v_fmac_f32_e32 v34, v57, v57
	ds_bpermute_b32 v35, v49, v34
	s_waitcnt lgkmcnt(0)
	v_add_f32_e32 v34, v34, v35
	ds_bpermute_b32 v35, v50, v34
	s_waitcnt lgkmcnt(0)
	v_add_f32_e32 v34, v34, v35
	ds_bpermute_b32 v35, v51, v34
	s_waitcnt lgkmcnt(0)
	v_add_f32_e32 v34, v34, v35
	ds_bpermute_b32 v35, v52, v34
	s_waitcnt lgkmcnt(0)
	v_add_f32_e32 v34, v34, v35
	ds_bpermute_b32 v35, v53, v34
	v_mul_f32_e32 v36, v36, v57
	ds_bpermute_b32 v37, v53, v36
	s_waitcnt lgkmcnt(0)
	v_mul_f32_e32 v37, v56, v37
	v_cndmask_b32_e64 v38, v37, -v37, s[38:39]
	v_fmac_f32_e32 v38, v55, v36
	v_lshl_add_u64 v[36:37], s[16:17], 0, v[28:29]
	global_store_dword v[36:37], v38, off
	s_and_saveexec_b64 s[4:5], s[42:43]
	s_cbranch_execz .LBB0_991
	s_add_u32 s6, s16, s3
	s_addc_u32 s7, s17, s9
	v_add_f32_e32 v34, v34, v35
	global_store_dword v99, v34, s[6:7]
	s_branch .LBB0_991
